# P2 work queue: next item claimed one item ahead (atomic round trip overlapped with the running item)
# speedup vs baseline: 1.0125x; 1.0125x over previous
.LBB0_86:
	ds_read_b128 v[4:7], v3
	v_add_u32_e32 v10, s14, v2
	v_add_u32_e32 v8, 0x80, v10
	v_ashrrev_i32_e32 v9, 31, v8
	s_add_i32 s14, s14, 64
	s_waitcnt lgkmcnt(0)
	v_cvt_pk_bf16_f32 v4, v4, v5
	v_cvt_pk_bf16_f32 v5, v6, v7
	v_lshlrev_b64 v[6:7], 11, v[8:9]
	v_lshl_add_u64 v[6:7], v[0:1], 0, v[6:7]
	global_store_dwordx2 v[6:7], v[4:5], off offset:256
	ds_read_b128 v[4:7], v3 offset:16640
	v_add_u32_e32 v8, 0x90, v10
	v_ashrrev_i32_e32 v9, 31, v8
	s_cmpk_lg_i32 s14, 0x80
	s_waitcnt lgkmcnt(0)
	v_cvt_pk_bf16_f32 v4, v4, v5
	v_cvt_pk_bf16_f32 v5, v6, v7
	v_lshlrev_b64 v[6:7], 11, v[8:9]
	v_lshl_add_u64 v[6:7], v[0:1], 0, v[6:7]
	global_store_dwordx2 v[6:7], v[4:5], off offset:256
	ds_read_b128 v[4:7], v3 offset:33280
	v_add_u32_e32 v8, 0xa0, v10
	v_ashrrev_i32_e32 v9, 31, v8
	s_waitcnt lgkmcnt(0)
	v_cvt_pk_bf16_f32 v4, v4, v5
	v_cvt_pk_bf16_f32 v5, v6, v7
	v_lshlrev_b64 v[6:7], 11, v[8:9]
	v_lshl_add_u64 v[6:7], v[0:1], 0, v[6:7]
	global_store_dwordx2 v[6:7], v[4:5], off offset:256
	ds_read_b128 v[4:7], v3 offset:49920
	v_add_u32_e32 v8, 0xb0, v10
	v_ashrrev_i32_e32 v9, 31, v8
	v_add_u32_e32 v3, 0x10400, v3
	s_waitcnt lgkmcnt(0)
	v_cvt_pk_bf16_f32 v4, v4, v5
	v_cvt_pk_bf16_f32 v5, v6, v7
	v_lshlrev_b64 v[6:7], 11, v[8:9]
	v_lshl_add_u64 v[6:7], v[0:1], 0, v[6:7]
	global_store_dwordx2 v[6:7], v[4:5], off offset:256
	s_cbranch_scc1 .LBB0_86
	s_barrier
	s_branch .LBB0_71
	s_nop 0
	s_nop 0
	s_nop 0
	s_nop 0
	s_nop 0
	s_nop 0
	s_nop 0
.LBB0_88:
	s_mov_b32 s84, 0
	s_mov_b32 s86, 0
	s_mov_b32 s54, 0
	s_mov_b32 s62, 0
	v_readlane_b32 s56, v255, 36
	s_mov_b64 s[14:15], 0
	s_mov_b32 s65, 0xffff
	s_mov_b32 s85, 0x40280000
	s_mov_b32 s87, 0x40340000
	s_mov_b32 s55, 0x40450000
	s_mov_b32 s63, 0x40710000
	v_readlane_b32 s57, v255, 37

.LBB0_104:
	s_movk_i32 s60, 0x140
	s_andn2_b64 vcc, exec, s[56:57]
	s_cbranch_vccnz .LBB0_201
	v_readlane_b32 s14, v254, 5
	v_readlane_b32 s15, v254, 6
	s_lshl_b32 s14, s14, 6
	s_ashr_i32 s15, s14, 31
	s_lshl_b64 s[14:15], s[14:15], 2
	s_add_u32 s88, s74, s14
	s_addc_u32 s89, s75, s15
	s_add_u32 s14, s74, 0x1c0000
	s_addc_u32 s15, s75, 0
	s_add_u32 s48, s74, 0x1c8000
	s_addc_u32 s49, s75, 0
	v_writelane_b32 v255, s14, 36
	s_add_u32 s44, s74, 0x1a0000
	s_addc_u32 s45, s75, 0
	v_writelane_b32 v255, s15, 37
	s_add_u32 s94, s74, 0x1a8000
	v_readlane_b32 s14, v255, 26
	v_cmp_eq_u32_e64 s[40:41], 0, v192
	s_addc_u32 s95, s75, 0
	s_lshl_b32 s61, s14, 6
	v_readlane_b32 s15, v255, 27
	s_and_saveexec_b64 s[14:15], s[40:41]
	v_mov_b32_e32 v250, 1
	global_atomic_add v251, v169, v250, s[88:89] offset:256 sc0
	s_or_b64 exec, exec, s[14:15]
	s_branch .LBB0_108

.LBB0_108:
	s_and_saveexec_b64 s[14:15], s[40:41]
	s_cbranch_execz .LBB0_112
	s_mov_b64 s[18:19], exec
	s_waitcnt vmcnt(7)
	v_mbcnt_lo_u32_b32 v0, s18, 0
	v_mbcnt_hi_u32_b32 v0, s19, v0
	v_cmp_eq_u32_e32 vcc, 0, v0
	s_and_saveexec_b64 s[16:17], vcc
	s_cbranch_execz .LBB0_111
	s_bcnt1_i32_b64 s5, s[18:19]
	s_waitcnt vmcnt(0)
	v_mov_b32_e32 v1, v251
	v_mov_b32_e32 v250, s5
	global_atomic_add v251, v169, v250, s[88:89] offset:256 sc0
.LBB0_111:
	s_or_b64 exec, exec, s[16:17]
	v_readfirstlane_b32 s5, v1
	s_nop 1
	v_add_u32_e32 v0, s5, v0
	ds_write_b32 v174, v0

.LBB0_209:
	s_and_b32 s55, s24, 3
	v_and_b32_e32 v7, 15, v6
	v_and_b32_e32 v135, 48, v6
	v_lshlrev_b32_e32 v6, 2, v6
	v_lshl_add_u64 v[8:9], s[40:41], 0, v[168:169]
	v_mov_b32_e32 v129, v169
	v_lshl_or_b32 v134, s27, 6, v7
	v_lshl_or_b32 v7, v7, 6, v135
	v_and_b32_e32 v6, 32, v6
	s_lshl_b32 s24, s27, 13
	s_lshl_b32 s27, s55, 12
	s_add_i32 s56, s16, 0x18000
	v_lshl_add_u64 v[10:11], s[40:41], 0, v[128:129]
	v_bitop3_b32 v136, v7, s27, v6 bitop3:0xde
	v_bitop3_b32 v137, v7, s24, v6 bitop3:0xde
	v_lshl_add_u64 v[6:7], v[8:9], 0, s[34:35]
	s_mov_b32 m0, s56
	s_add_i32 s85, s16, 0x1a000
	v_lshl_add_u64 v[12:13], s[42:43], 0, v[168:169]
	s_and_b32 s57, s62, 7
	global_load_lds_dwordx4 v[6:7], off
	v_lshl_add_u64 v[6:7], v[10:11], 0, s[34:35]
	s_mov_b32 m0, s85
	s_add_i32 s86, s16, 0x8000
	s_add_i32 s87, s16, 0xa000
	v_lshl_add_u64 v[14:15], s[42:43], 0, v[128:129]
	global_load_lds_dwordx4 v[6:7], off
	v_lshl_add_u64 v[6:7], v[12:13], 0, s[34:35]
	s_mov_b32 m0, s86
	s_add_u32 s36, s40, 0x40080
	global_load_lds_dwordx4 v[6:7], off
	v_lshl_add_u64 v[6:7], v[14:15], 0, s[34:35]
	s_mov_b32 m0, s87
	s_addc_u32 s37, s41, 0
	s_add_i32 s90, s16, 0x1c000
	global_load_lds_dwordx4 v[6:7], off
	v_lshl_add_u64 v[6:7], s[36:37], 0, v[168:169]
	s_mov_b32 m0, s90
	s_add_i32 s24, s16, 0x1e000
	global_load_lds_dwordx4 v[6:7], off
	v_lshl_add_u64 v[6:7], s[36:37], 0, v[128:129]
	s_mov_b32 m0, s24
	s_add_i32 s26, s26, s57
	global_load_lds_dwordx4 v[6:7], off
	s_waitcnt vmcnt(8)
	s_barrier
	s_ashr_i32 s27, s26, 31
	s_lshl_b64 s[26:27], s[26:27], 19
	v_lshlrev_b32_e32 v6, 14, v0
	s_add_u32 s60, s74, s26
	v_and_b32_e32 v6, 0xffff8000, v6
	s_addc_u32 s91, s75, s27
	v_lshl_add_u32 v1, v1, 11, v6
	v_and_b32_e32 v0, 1, v0
	v_lshl_or_b32 v0, v0, 6, v1
	s_add_u32 s26, s18, s26
	v_lshl_add_u32 v0, v3, 1, v0
	v_mov_b32_e32 v1, v169
	s_addc_u32 s27, s19, s27
	v_lshl_add_u64 v[130:131], s[26:27], 0, v[0:1]
	v_lshlrev_b32_e32 v0, 14, v2
	v_and_b32_e32 v0, 0xffff8000, v0
	v_lshl_add_u32 v0, v4, 11, v0
	v_and_b32_e32 v1, 1, v2
	v_lshl_or_b32 v0, v1, 6, v0
	s_waitcnt vmcnt(6)
	v_lshl_add_u32 v0, v5, 1, v0
	v_mov_b32_e32 v1, v169
	v_lshl_add_u64 v[132:133], s[26:27], 0, v[0:1]
	s_add_u32 s92, s30, s14
	v_mov_b32_e32 v0, 0
	s_addc_u32 s93, s61, s15
	s_mov_b32 s94, -2
	s_mov_b64 s[44:45], 0
	v_mov_b32_e32 v1, v0
	v_mov_b32_e32 v2, v0
	v_mov_b32_e32 v3, v0
	v_mov_b32_e32 v4, v0
	v_mov_b32_e32 v5, v0
	v_mov_b32_e32 v6, v0
	v_mov_b32_e32 v7, v0
	v_mov_b32_e32 v8, v0
	v_mov_b32_e32 v9, v0
	v_mov_b32_e32 v10, v0
	v_mov_b32_e32 v11, v0
	v_mov_b32_e32 v12, v0
	v_mov_b32_e32 v13, v0
	v_mov_b32_e32 v14, v0
	v_mov_b32_e32 v15, v0
	v_mov_b32_e32 v16, v0
	v_mov_b32_e32 v17, v0
	v_mov_b32_e32 v18, v0
	v_mov_b32_e32 v19, v0
	v_mov_b32_e32 v20, v0
	v_mov_b32_e32 v21, v0
	v_mov_b32_e32 v22, v0
	v_mov_b32_e32 v23, v0
	v_mov_b32_e32 v24, v0
	v_mov_b32_e32 v25, v0
	v_mov_b32_e32 v26, v0
	v_mov_b32_e32 v27, v0
	v_mov_b32_e32 v28, v0
	v_mov_b32_e32 v29, v0
	v_mov_b32_e32 v30, v0
	v_mov_b32_e32 v31, v0
	v_mov_b32_e32 v32, v0
	v_mov_b32_e32 v33, v0
	v_mov_b32_e32 v34, v0
	v_mov_b32_e32 v35, v0
	v_mov_b32_e32 v36, v0
	v_mov_b32_e32 v37, v0
	v_mov_b32_e32 v38, v0
	v_mov_b32_e32 v39, v0
	v_mov_b32_e32 v40, v0
	v_mov_b32_e32 v41, v0
	v_mov_b32_e32 v42, v0
	v_mov_b32_e32 v43, v0
	v_mov_b32_e32 v44, v0
	v_mov_b32_e32 v45, v0
	v_mov_b32_e32 v46, v0
	v_mov_b32_e32 v47, v0
	v_mov_b32_e32 v48, v0
	v_mov_b32_e32 v49, v0
	v_mov_b32_e32 v50, v0
	v_mov_b32_e32 v51, v0
	v_mov_b32_e32 v52, v0
	v_mov_b32_e32 v53, v0
	v_mov_b32_e32 v54, v0
	v_mov_b32_e32 v55, v0
	v_mov_b32_e32 v56, v0
	v_mov_b32_e32 v57, v0
	v_mov_b32_e32 v58, v0
	v_mov_b32_e32 v59, v0
	v_mov_b32_e32 v60, v0
	v_mov_b32_e32 v61, v0
	v_mov_b32_e32 v62, v0
	v_mov_b32_e32 v63, v0
	v_mov_b32_e32 v64, v0
	v_mov_b32_e32 v65, v0
	v_mov_b32_e32 v66, v0
	v_mov_b32_e32 v67, v0
	v_mov_b32_e32 v68, v0
	v_mov_b32_e32 v69, v0
	v_mov_b32_e32 v70, v0
	v_mov_b32_e32 v71, v0
	v_mov_b32_e32 v72, v0
	v_mov_b32_e32 v73, v0
	v_mov_b32_e32 v74, v0
	v_mov_b32_e32 v75, v0
	v_mov_b32_e32 v76, v0
	v_mov_b32_e32 v77, v0
	v_mov_b32_e32 v78, v0
	v_mov_b32_e32 v79, v0
	v_mov_b32_e32 v80, v0
	v_mov_b32_e32 v81, v0
	v_mov_b32_e32 v82, v0
	v_mov_b32_e32 v83, v0
	v_mov_b32_e32 v84, v0
	v_mov_b32_e32 v85, v0
	v_mov_b32_e32 v86, v0
	v_mov_b32_e32 v87, v0
	v_mov_b32_e32 v88, v0
	v_mov_b32_e32 v89, v0
	v_mov_b32_e32 v90, v0
	v_mov_b32_e32 v91, v0
	v_mov_b32_e32 v92, v0
	v_mov_b32_e32 v93, v0
	v_mov_b32_e32 v94, v0
	v_mov_b32_e32 v95, v0
	v_mov_b32_e32 v96, v0
	v_mov_b32_e32 v97, v0
	v_mov_b32_e32 v98, v0
	v_mov_b32_e32 v99, v0
	v_mov_b32_e32 v100, v0
	v_mov_b32_e32 v101, v0
	v_mov_b32_e32 v102, v0
	v_mov_b32_e32 v103, v0
	v_mov_b32_e32 v104, v0
	v_mov_b32_e32 v105, v0
	v_mov_b32_e32 v106, v0
	v_mov_b32_e32 v107, v0
	v_mov_b32_e32 v108, v0
	v_mov_b32_e32 v109, v0
	v_mov_b32_e32 v110, v0
	v_mov_b32_e32 v111, v0
	v_mov_b32_e32 v112, v0
	v_mov_b32_e32 v113, v0
	v_mov_b32_e32 v114, v0
	v_mov_b32_e32 v115, v0
	v_mov_b32_e32 v116, v0
	v_mov_b32_e32 v117, v0
	v_mov_b32_e32 v118, v0
	v_mov_b32_e32 v119, v0
	v_mov_b32_e32 v120, v0
	v_mov_b32_e32 v121, v0
	v_mov_b32_e32 v122, v0
	v_mov_b32_e32 v123, v0
	v_mov_b32_e32 v124, v0
	v_mov_b32_e32 v125, v0
	v_mov_b32_e32 v126, v0
	v_mov_b32_e32 v127, v0
	s_nop 0
	s_nop 0
	s_nop 0
	s_nop 0
	s_nop 0
	s_nop 0
	s_nop 0
	s_nop 0
	s_nop 0
	s_nop 0
	s_nop 0
	s_nop 0
	s_nop 0
	s_nop 0
	s_barrier
